# ssd_out phase tile loop: kernarg pointer loads for conv weights hoisted to the tile top next to the dt pointer load; dead A_log pointer load removed
# speedup vs baseline: 1.0013x; 1.0013x over previous
.LBB0_1695:
	v_mov_b32_e32 v134, v252
	s_barrier
	s_load_dwordx2 s[54:55], s[0:1], 0xd0
	v_and_b32_e32 v135, 63, v134
	s_lshl_b32 s15, s52, 6
	v_readfirstlane_b32 s16, v134
	v_or_b32_e32 v0, s15, v135
	s_ashr_i32 s58, s16, 6
	v_ashrrev_i32_e32 v1, 31, v0
	s_ashr_i32 s59, s58, 31
	v_lshlrev_b64 v[0:1], 5, v[0:1]
	s_waitcnt lgkmcnt(0)
	v_lshl_add_u64 v[0:1], s[54:55], 0, v[0:1]
	s_lshl_b64 s[36:37], s[58:59], 2
	v_lshl_add_u64 v[0:1], v[0:1], 0, s[36:37]
	s_mov_b32 s2, 0x22e0000
	v_add_co_u32_e32 v0, vcc, s2, v0
	s_load_dwordx2 s[2:3], s[0:1], 0x60
	s_load_dwordx2 s[98:99], s[0:1], 0x68
	s_load_dwordx4 s[44:47], s[0:1], 0x50
	s_nop 0
	v_addc_co_u32_e32 v1, vcc, 0, v1, vcc
	global_load_dword v0, v[0:1], off
	s_waitcnt lgkmcnt(0)
	s_add_u32 s2, s2, s36
	s_addc_u32 s3, s3, s37
	global_load_dword v1, v137, s[2:3]
	s_add_u32 s98, s98, s36
	s_addc_u32 s99, s99, s37
	global_load_dword v250, v137, s[98:99]
	s_mov_b32 s2, 0x41a00000
	s_waitcnt vmcnt(0)
	v_add_f32_e32 v0, v0, v1
	v_cmp_nlt_f32_e32 vcc, s2, v0
	s_and_saveexec_b64 s[2:3], vcc
	s_cbranch_execz .LBB0_1697
	v_mul_f32_e32 v1, 0x3fb8aa3b, v0
	v_rndne_f32_e32 v2, v1
	v_sub_f32_e32 v3, v1, v2
	v_fma_f32 v1, v0, s8, -v1
	v_fmac_f32_e32 v1, 0x32a5705f, v0
	v_add_f32_e32 v1, v3, v1
	v_cvt_i32_f32_e32 v2, v2
	v_exp_f32_e32 v1, v1
	v_cmp_ngt_f32_e32 vcc, s9, v0
	s_mov_b32 s4, 0x3f2aaaab
	v_ldexp_f32 v1, v1, v2
	v_cndmask_b32_e32 v1, 0, v1, vcc
	v_cmp_nlt_f32_e32 vcc, s10, v0
	s_nop 1
	v_cndmask_b32_e32 v14, v183, v1, vcc
	v_add_f32_e32 v2, 1.0, v14
	v_add_f32_e32 v0, -1.0, v2
	v_sub_f32_e32 v1, v0, v2
	v_add_f32_e32 v1, 1.0, v1
	v_sub_f32_e32 v0, v14, v0
	v_add_f32_e32 v3, v0, v1
	v_frexp_mant_f32_e32 v4, v2
	v_cvt_f64_f32_e32 v[0:1], v2
	v_frexp_exp_i32_f64_e32 v0, v[0:1]
	v_cmp_gt_f32_e32 vcc, s4, v4
	s_mov_b32 s4, 0x3f317218
	s_nop 0
	v_subbrev_co_u32_e32 v8, vcc, 0, v0, vcc
	v_sub_u32_e32 v0, 0, v8
	v_ldexp_f32 v1, v2, v0
	v_add_f32_e32 v2, -1.0, v1
	v_add_f32_e32 v4, 1.0, v1
	v_ldexp_f32 v0, v3, v0
	v_add_f32_e32 v3, 1.0, v2
	v_add_f32_e32 v5, -1.0, v4
	v_sub_f32_e32 v3, v1, v3
	v_sub_f32_e32 v1, v1, v5
	v_add_f32_e32 v3, v0, v3
	v_add_f32_e32 v0, v0, v1
	v_add_f32_e32 v9, v4, v0
	v_rcp_f32_e32 v11, v9
	v_sub_f32_e32 v1, v4, v9
	v_add_f32_e32 v10, v0, v1
	v_add_f32_e32 v1, v2, v3
	v_mul_f32_e32 v13, v1, v11
	v_sub_f32_e32 v0, v2, v1
	v_mul_f32_e32 v2, v9, v13
	v_fma_f32 v4, v13, v9, -v2
	v_fmac_f32_e32 v4, v13, v10
	v_add_f32_e32 v12, v3, v0
	v_add_f32_e32 v0, v2, v4
	v_sub_f32_e32 v3, v1, v0
	v_pk_add_f32 v[6:7], v[0:1], v[2:3] neg_lo:[0,1] neg_hi:[0,1]
	v_mov_b32_e32 v5, v0
	v_pk_add_f32 v[0:1], v[6:7], v[4:5] neg_lo:[0,1] neg_hi:[0,1]
	s_nop 0
	v_add_f32_e32 v1, v12, v1
	v_add_f32_e32 v0, v0, v1
	v_add_f32_e32 v1, v3, v0
	v_mul_f32_e32 v12, v11, v1
	v_mul_f32_e32 v2, v9, v12
	v_fma_f32 v4, v12, v9, -v2
	v_fmac_f32_e32 v4, v12, v10
	v_sub_f32_e32 v3, v3, v1
	v_add_f32_e32 v9, v0, v3
	v_add_f32_e32 v0, v2, v4
	v_sub_f32_e32 v3, v1, v0
	v_pk_add_f32 v[6:7], v[0:1], v[2:3] neg_lo:[0,1] neg_hi:[0,1]
	v_mov_b32_e32 v5, v0
	v_pk_add_f32 v[0:1], v[6:7], v[4:5] neg_lo:[0,1] neg_hi:[0,1]
	s_nop 0
	v_add_f32_e32 v1, v9, v1
	v_add_f32_e32 v0, v0, v1
	v_add_f32_e32 v1, v13, v12
	v_add_f32_e32 v0, v3, v0
	v_sub_f32_e32 v2, v1, v13
	v_mul_f32_e32 v0, v11, v0
	v_sub_f32_e32 v2, v12, v2
	v_add_f32_e32 v2, v2, v0
	v_add_f32_e32 v4, v1, v2
	v_mul_f32_e32 v5, v4, v4
	v_fmamk_f32 v0, v5, 0x3e9b6dac, v180
	v_fmaak_f32 v139, v5, v0, 0x3f2aaada
	v_cvt_f32_i32_e32 v0, v8
	v_sub_f32_e32 v1, v4, v1
	v_sub_f32_e32 v1, v2, v1
	v_ldexp_f32 v6, v1, 1
	v_mul_f32_e32 v1, v4, v5
	v_ldexp_f32 v3, v4, 1
	v_pk_mul_f32 v[4:5], v[0:1], v[138:139]
	s_nop 0
	v_fma_f32 v2, v0, s4, -v4
	v_fmac_f32_e32 v2, 0xb102e308, v0
	v_pk_add_f32 v[0:1], v[4:5], v[2:3]
	s_mov_b32 s4, 0x7f800000
	v_sub_f32_e32 v3, v1, v3
	v_sub_f32_e32 v3, v5, v3
	v_add_f32_e32 v7, v6, v3
	v_mov_b32_e32 v6, v4
	v_pk_add_f32 v[4:5], v[0:1], v[4:5] neg_lo:[0,1] neg_hi:[0,1]
	v_pk_add_f32 v[8:9], v[0:1], v[6:7]
	v_mov_b32_e32 v3, v0
	v_mov_b32_e32 v5, v9
	v_pk_add_f32 v[10:11], v[2:3], v[4:5] neg_lo:[0,1] neg_hi:[0,1]
	v_pk_add_f32 v[2:3], v[2:3], v[4:5]
	v_mov_b32_e32 v6, v7
	v_pk_add_f32 v[4:5], v[2:3], v[0:1] op_sel:[1,0] op_sel_hi:[0,1] neg_lo:[0,1] neg_hi:[0,1]
	v_pk_add_f32 v[12:13], v[8:9], v[4:5] op_sel_hi:[1,0] neg_lo:[0,1] neg_hi:[0,1]
	v_mov_b32_e32 v8, v9
	v_mov_b32_e32 v9, v3
	v_pk_mov_b32 v[4:5], v[0:1], v[4:5] op_sel:[1,0]
	v_mov_b32_e32 v7, v0
	v_pk_add_f32 v[4:5], v[8:9], v[4:5] neg_lo:[0,1] neg_hi:[0,1]
	v_mov_b32_e32 v12, v10
	v_pk_add_f32 v[0:1], v[6:7], v[4:5] neg_lo:[0,1] neg_hi:[0,1]
	v_mov_b32_e32 v11, v3
	v_pk_add_f32 v[4:5], v[12:13], v[0:1]
	v_cmp_neq_f32_e32 vcc, s4, v14
	v_pk_add_f32 v[6:7], v[4:5], v[4:5] op_sel:[0,1] op_sel_hi:[1,0]
	s_mov_b32 s4, 0x33800000
	v_pk_add_f32 v[2:3], v[2:3], v[6:7] op_sel:[1,0] op_sel_hi:[0,1]
	v_mov_b32_e32 v5, v2
	v_pk_add_f32 v[8:9], v[4:5], v[10:11] neg_lo:[0,1] neg_hi:[0,1]
	v_mov_b32_e32 v1, v6
	v_sub_f32_e32 v3, v4, v8
	v_pk_add_f32 v[0:1], v[0:1], v[8:9] neg_lo:[0,1] neg_hi:[0,1]
	v_sub_f32_e32 v3, v10, v3
	v_add_f32_e32 v0, v0, v3
	v_add_f32_e32 v0, v0, v1
	v_add_f32_e32 v0, v2, v0
	v_cndmask_b32_e32 v0, v183, v0, vcc
	v_cmp_lt_f32_e64 vcc, |v14|, s4
	s_nop 1
	v_cndmask_b32_e32 v0, v0, v14, vcc
.LBB0_1697:
	s_or_b64 exec, exec, s[2:3]
	s_and_b32 s2, s52, 0x7f
	s_cmp_lg_u32 s2, 0
	s_cselect_b64 s[2:3], -1, 0
	v_mov_b32_e32 v1, v250
	v_and_b32_e32 v139, 64, v184
	v_add_u32_e32 v2, -1, v184
	v_add_u32_e32 v3, -2, v184
	v_cmp_lt_i32_e32 vcc, v2, v139
	v_add_u32_e32 v4, -4, v184
	v_add_u32_e32 v5, -8, v184
	v_cndmask_b32_e32 v2, v2, v184, vcc
	v_cmp_lt_i32_e32 vcc, v3, v139
	v_lshlrev_b32_e32 v2, 2, v2
	v_add_u32_e32 v6, -16, v184
	v_cndmask_b32_e32 v3, v3, v184, vcc
	v_cmp_lt_i32_e32 vcc, v4, v139
	v_subrev_u32_e32 v7, 32, v184
	v_lshlrev_b32_e32 v3, 2, v3
	v_cndmask_b32_e32 v4, v4, v184, vcc
	v_cmp_lt_i32_e32 vcc, v5, v139
	v_cmp_gt_u32_e64 s[42:43], 8, v135
	v_and_b32_e32 v120, 0x7f, v134
	v_cndmask_b32_e32 v5, v5, v184, vcc
	v_lshlrev_b32_e32 v136, 5, v120
	s_mov_b64 s[4:5], 0x1000
	s_and_b32 s56, s16, 0xffffffc0
	v_or_b32_e32 v14, s56, v135
	v_ashrrev_i32_e32 v40, 3, v134
	s_waitcnt vmcnt(0)
	v_mul_f32_e32 v8, 0x3fb8aa3b, v1
	v_fma_f32 v9, v1, s8, -v8
	v_rndne_f32_e32 v10, v8
	v_fmac_f32_e32 v9, 0x32a5705f, v1
	v_sub_f32_e32 v8, v8, v10
	v_add_f32_e32 v8, v8, v9
	v_cvt_i32_f32_e32 v10, v10
	v_exp_f32_e32 v8, v8
	v_cmp_ngt_f32_e32 vcc, s9, v1
	v_ldexp_f32 v8, v8, v10
	s_nop 0
	v_cndmask_b32_e32 v8, 0, v8, vcc
	v_cmp_nlt_f32_e32 vcc, s10, v1
	s_nop 1
	v_cndmask_b32_e32 v1, v183, v8, vcc
	v_mul_f32_e64 v8, v0, -v1
	ds_bpermute_b32 v2, v2, v8
	v_cmp_lt_i32_e32 vcc, v6, v139
	s_waitcnt lgkmcnt(0)
	v_fma_f32 v1, v0, -v1, v2
	v_cndmask_b32_e32 v6, v6, v184, vcc
	v_cmp_lt_i32_e32 vcc, v7, v139
	v_lshlrev_b32_e32 v12, 2, v6
	s_nop 0
	v_cndmask_b32_e32 v7, v7, v184, vcc
	v_cmp_eq_u32_e32 vcc, 0, v135
	v_lshlrev_b32_e32 v13, 2, v7
	s_nop 0
	v_cndmask_b32_e32 v1, v1, v8, vcc
	ds_bpermute_b32 v2, v3, v1
	v_cmp_gt_u32_e32 vcc, 2, v135
	v_lshlrev_b32_e32 v3, 2, v4
	v_lshlrev_b32_e32 v8, 2, v5
	s_waitcnt lgkmcnt(0)
	v_add_f32_e32 v2, v1, v2
	v_cndmask_b32_e32 v1, v2, v1, vcc
	ds_bpermute_b32 v6, v3, v1
	v_cmp_gt_u32_e32 vcc, 4, v135
	v_lshl_add_u64 v[2:3], s[44:45], 0, v[136:137]
	v_lshl_add_u64 v[4:5], v[2:3], 0, s[4:5]
	s_movk_i32 s4, 0x2000
	s_waitcnt lgkmcnt(0)
	v_add_f32_e32 v6, v1, v6
	v_cndmask_b32_e32 v1, v6, v1, vcc
	ds_bpermute_b32 v7, v8, v1
	v_add_co_u32_e32 v6, vcc, s4, v2
	s_mov_b64 s[4:5], 0x2000
	v_lshl_add_u64 v[8:9], v[2:3], 0, s[4:5]
	s_waitcnt lgkmcnt(0)
	v_add_f32_e32 v7, v1, v7
	v_cndmask_b32_e64 v1, v7, v1, s[42:43]
	ds_bpermute_b32 v15, v12, v1
	s_mov_b64 s[4:5], 0x3000
	v_addc_co_u32_e32 v7, vcc, 0, v3, vcc
	v_lshl_add_u64 v[10:11], v[2:3], 0, s[4:5]
	v_add_co_u32_e32 v12, vcc, 0x3000, v2
	v_lshl_add_u32 v2, v14, 2, 0
	s_waitcnt lgkmcnt(0)
	v_add_f32_e32 v14, v1, v15
	v_cmp_gt_u32_e64 s[42:43], 16, v135
	s_mov_b64 s[4:5], 0
	s_nop 0
	v_cndmask_b32_e64 v1, v14, v1, s[42:43]
	ds_bpermute_b32 v14, v13, v1
	v_addc_co_u32_e32 v13, vcc, 0, v3, vcc
	v_add_u32_e32 v3, 0x20800, v2
	ds_write_b32 v3, v0
	s_waitcnt lgkmcnt(1)
	v_add_f32_e32 v0, v1, v14
	v_cmp_gt_u32_e64 s[42:43], 32, v135
	v_add_u32_e32 v2, 0x21000, v2
	v_cmp_gt_i32_e32 vcc, 16, v40
	v_cndmask_b32_e64 v0, v0, v1, s[42:43]
	ds_write_b32 v2, v0
	s_waitcnt lgkmcnt(0)
	s_barrier
	global_load_dwordx4 v[24:27], v[6:7], off offset:-4096
	global_load_dwordx4 v[20:23], v[6:7], off
	global_load_dwordx4 v[0:3], v[4:5], off offset:16
	s_nop 0
	global_load_dwordx4 v[4:7], v[8:9], off offset:16
	global_load_dwordx4 v[28:31], v[12:13], off
	s_nop 0
	global_load_dwordx4 v[8:11], v[10:11], off offset:16
	s_nop 0
	global_load_dwordx4 v[12:15], v136, s[44:45] offset:16
	global_load_dwordx4 v[16:19], v136, s[46:47] offset:16
	global_load_dwordx4 v[32:35], v136, s[44:45]
	global_load_dwordx4 v[36:39], v136, s[46:47]
	s_and_saveexec_b64 s[6:7], vcc
	s_xor_b64 s[6:7], exec, s[6:7]
	s_and_b64 s[4:5], s[2:3], exec
	s_or_saveexec_b64 s[6:7], s[6:7]
	v_and_b32_e32 v121, -16, v40
	s_xor_b64 exec, exec, s[6:7]
	s_movk_i32 s17, 0x43
	v_cmp_gt_i32_e64 s[44:45], s17, v121
	s_andn2_b64 s[4:5], s[4:5], exec
	s_and_b64 s[18:19], s[44:45], exec
	s_or_b64 s[4:5], s[4:5], s[18:19]
	s_or_b64 exec, exec, s[6:7]
	v_lshlrev_b32_e32 v136, 4, v120
	v_lshl_add_u64 v[42:43], s[54:55], 0, v[136:137]
	s_mov_b64 s[6:7], 0xf77e200
	v_lshl_add_u64 v[116:117], v[42:43], 0, s[6:7]
	v_mov_b32_e32 v100, 0
	v_mov_b32_e32 v101, 0
	v_mov_b32_e32 v102, 0
	v_mov_b32_e32 v103, 0
	s_and_saveexec_b64 s[6:7], s[4:5]
	s_cbranch_execz .LBB0_1703
	v_add3_u32 v42, s15, -3, v121
	v_ashrrev_i32_e32 v43, 31, v42
	v_lshlrev_b64 v[42:43], 11, v[42:43]
	v_lshl_add_u64 v[42:43], v[116:117], 0, v[42:43]
	global_load_dwordx4 v[100:103], v[42:43], off
